# short-conv section de-serialised: all 24 loads of an item issued upfront, counted vmcnt per row (was 10 dependent round trips); + earlier stack
# speedup vs baseline: 1.0083x; 1.0026x over previous
; __device__ __forceinline__ u32x4 pack8(const float (&f)[8]) { u32x4 w; w.x = pk2(f[0], f[1]); w.y = pk2(f[2], f[3]); w.z = pk2(f[4], f[5]); w.w = pk2(f[6], f[7]); return w; }
; __device__ __forceinline__ void phase3(const Params& p, LAS unsigned char* lds, int tid, int lane, int wave) {
;     ...
;     for (int it = bx * 512 + tid; it < (T_ / 8) * 64; it += G * 512) {
;         const int rc = it >> 6, c0 = 8 * (it & 63), t0 = 8 * rc;
;         float w0[8], w1[8], w2[8], z1[8], z2[8];
; #pragma unroll
;         for (int i = 0; i < 8; ++i) { w0[i] = p.cmw[c0 + i]; w1[i] = p.cmw[512 + c0 + i]; w2[i] = p.cmw[1024 + c0 + i]; z1[i] = 0.f; z2[i] = 0.f; }
;         if (t0 & (S_ - 1)) { unpack8(*(const u32x4*)(Z + (size_t)(t0 - 2) * 512 + c0), z2); unpack8(*(const u32x4*)(Z + (size_t)(t0 - 1) * 512 + c0), z1); }
; #pragma unroll
;         for (int r = 0; r < 8; ++r) { float zc[8], bg[8], ov[8];
;             unpack8(*(const u32x4*)(Z + (size_t)(t0 + r) * 512 + c0), zc); unpack8(*(const u32x4*)(BG + (size_t)(t0 + r) * 512 + c0), bg);
; #pragma unroll
;             for (int i = 0; i < 8; ++i) { ov[i] = bg[i] * (w0[i] * z2[i] + w1[i] * z1[i] + w2[i] * zc[i]); z2[i] = z1[i]; z1[i] = zc[i]; }
;             st16wt(mix, (unsigned)(((t0 + r) * D_ + 512 + c0) * 2), pack8(ov)); }
.LBB0_382:
	s_mov_b64 s[6:7], exec
	s_lshl_b32 s4, s2, 9
	s_lshl_b32 s5, s26, 9
	s_add_u32 s16, s14, 0x7000000
	s_addc_u32 s17, s15, 0
	s_add_u32 s18, s14, 0x8000000
	s_addc_u32 s19, s15, 0
	s_add_u32 s8, s14, 0x9000000
	s_addc_u32 s0, s15, 0
	s_and_b32 s9, s0, 0xffff
	s_brev_b32 s10, -2
	s_mov_b32 s11, 0x20000
.Lconv_loop:
	s_cmp_ge_u32 s4, 0x20000
	s_cbranch_scc1 .LBB0_387
	v_add_u32_e32 v4, s4, v208
	v_and_b32_e32 v32, 63, v4
	v_lshrrev_b32_e32 v7, 6, v4
	v_lshlrev_b32_e32 v5, 5, v32
	v_lshlrev_b32_e32 v32, 4, v32
	v_add_u32_e32 v6, 0x1000, v5
	global_load_dwordx4 v[8:11], v5, s[12:13]
	global_load_dwordx4 v[12:15], v5, s[12:13] offset:16
	global_load_dwordx4 v[16:19], v5, s[12:13] offset:2048
	global_load_dwordx4 v[20:23], v5, s[12:13] offset:2064
	global_load_dwordx4 v[24:27], v6, s[12:13]
	global_load_dwordx4 v[28:31], v6, s[12:13] offset:16
	v_lshl_or_b32 v33, v7, 13, v32
	v_add_u32_e32 v34, 0x1000, v33
	v_and_b32_e32 v35, 0xff, v7
	v_mov_b32_e32 v36, 0
	v_mov_b32_e32 v37, 0
	v_mov_b32_e32 v38, 0
	v_mov_b32_e32 v39, 0
	v_mov_b32_e32 v40, 0
	v_mov_b32_e32 v41, 0
	v_mov_b32_e32 v42, 0
	v_mov_b32_e32 v43, 0
	v_cmp_ne_u32_e32 vcc, 0, v35
	s_and_saveexec_b64 s[20:21], vcc
	global_load_dwordx4 v[36:39], v33, s[16:17] offset:-2048
	global_load_dwordx4 v[40:43], v33, s[16:17] offset:-1024
	s_or_b64 exec, exec, s[20:21]
	global_load_dwordx4 v[44:47], v33, s[16:17]
	global_load_dwordx4 v[48:51], v33, s[18:19]
	global_load_dwordx4 v[52:55], v33, s[16:17] offset:1024
	global_load_dwordx4 v[56:59], v33, s[18:19] offset:1024
	global_load_dwordx4 v[60:63], v33, s[16:17] offset:2048
	global_load_dwordx4 v[64:67], v33, s[18:19] offset:2048
	global_load_dwordx4 v[68:71], v33, s[16:17] offset:3072
	global_load_dwordx4 v[72:75], v33, s[18:19] offset:3072
	global_load_dwordx4 v[76:79], v34, s[16:17]
	global_load_dwordx4 v[80:83], v34, s[18:19]
	global_load_dwordx4 v[84:87], v34, s[16:17] offset:1024
	global_load_dwordx4 v[88:91], v34, s[18:19] offset:1024
	global_load_dwordx4 v[92:95], v34, s[16:17] offset:2048
	global_load_dwordx4 v[96:99], v34, s[18:19] offset:2048
	global_load_dwordx4 v[100:103], v34, s[16:17] offset:3072
	global_load_dwordx4 v[104:107], v34, s[18:19] offset:3072
	v_lshl_or_b32 v35, v7, 14, v32
	v_add_u32_e32 v35, 0x400, v35
	s_waitcnt vmcnt(16)
	v_lshlrev_b32_e32 v116, 16, v36
	v_and_b32_e32 v117, 0xffff0000, v36
	v_lshlrev_b32_e32 v118, 16, v37
	v_and_b32_e32 v119, 0xffff0000, v37
	v_lshlrev_b32_e32 v120, 16, v38
	v_and_b32_e32 v121, 0xffff0000, v38
	v_lshlrev_b32_e32 v122, 16, v39
	v_and_b32_e32 v123, 0xffff0000, v39
	v_lshlrev_b32_e32 v124, 16, v40
	v_and_b32_e32 v125, 0xffff0000, v40
	v_lshlrev_b32_e32 v126, 16, v41
	v_and_b32_e32 v127, 0xffff0000, v41
	v_lshlrev_b32_e32 v128, 16, v42
	v_and_b32_e32 v129, 0xffff0000, v42
	v_lshlrev_b32_e32 v130, 16, v43
	v_and_b32_e32 v131, 0xffff0000, v43
	s_waitcnt vmcnt(14)
	v_lshlrev_b32_e32 v108, 16, v44
	v_and_b32_e32 v109, 0xffff0000, v44
	v_lshlrev_b32_e32 v110, 16, v45
	v_and_b32_e32 v111, 0xffff0000, v45
	v_lshlrev_b32_e32 v112, 16, v46
	v_and_b32_e32 v113, 0xffff0000, v46
	v_lshlrev_b32_e32 v114, 16, v47
	v_and_b32_e32 v115, 0xffff0000, v47
	v_lshlrev_b32_e32 v132, 16, v48
	v_and_b32_e32 v133, 0xffff0000, v48
	v_lshlrev_b32_e32 v134, 16, v49
	v_and_b32_e32 v135, 0xffff0000, v49
	v_lshlrev_b32_e32 v136, 16, v50
	v_and_b32_e32 v137, 0xffff0000, v50
	v_lshlrev_b32_e32 v138, 16, v51
	v_and_b32_e32 v139, 0xffff0000, v51
	v_mul_f32_e32 v140, v16, v124
	v_mul_f32_e32 v141, v17, v125
	v_mul_f32_e32 v142, v18, v126
	v_mul_f32_e32 v143, v19, v127
	v_mul_f32_e32 v144, v20, v128
	v_mul_f32_e32 v145, v21, v129
	v_mul_f32_e32 v146, v22, v130
	v_mul_f32_e32 v147, v23, v131
	v_mul_f32_e32 v148, v24, v108
	v_mul_f32_e32 v149, v25, v109
	v_mul_f32_e32 v150, v26, v110
	v_mul_f32_e32 v151, v27, v111
	v_mul_f32_e32 v152, v28, v112
	v_mul_f32_e32 v153, v29, v113
	v_mul_f32_e32 v154, v30, v114
	v_mul_f32_e32 v155, v31, v115
	v_fma_f32 v140, v8, v116, v140
	v_fma_f32 v141, v9, v117, v141
	v_fma_f32 v142, v10, v118, v142
	v_fma_f32 v143, v11, v119, v143
	v_fma_f32 v144, v12, v120, v144
	v_fma_f32 v145, v13, v121, v145
	v_fma_f32 v146, v14, v122, v146
	v_fma_f32 v147, v15, v123, v147
	v_add_f32_e32 v140, v140, v148
	v_add_f32_e32 v141, v141, v149
	v_add_f32_e32 v142, v142, v150
	v_add_f32_e32 v143, v143, v151
	v_add_f32_e32 v144, v144, v152
	v_add_f32_e32 v145, v145, v153
	v_add_f32_e32 v146, v146, v154
	v_add_f32_e32 v147, v147, v155
	v_mul_f32_e32 v140, v140, v132
	v_mul_f32_e32 v141, v141, v133
	v_mul_f32_e32 v142, v142, v134
	v_mul_f32_e32 v143, v143, v135
	v_mul_f32_e32 v144, v144, v136
	v_mul_f32_e32 v145, v145, v137
	v_mul_f32_e32 v146, v146, v138
	v_mul_f32_e32 v147, v147, v139
	v_cvt_pk_bf16_f32 v156, v140, v141
	v_cvt_pk_bf16_f32 v157, v142, v143
	v_cvt_pk_bf16_f32 v158, v144, v145
	v_cvt_pk_bf16_f32 v159, v146, v147
	buffer_store_dwordx4 v[156:159], v35, s[8:11], 0 offen sc1
	s_waitcnt vmcnt(13)
; __device__ __forceinline__ u32x4 pack8(const float (&f)[8]) { u32x4 w; w.x = pk2(f[0], f[1]); w.y = pk2(f[2], f[3]); w.z = pk2(f[4], f[5]); w.w = pk2(f[6], f[7]); return w; }
; __device__ __forceinline__ void phase3(const Params& p, LAS unsigned char* lds, int tid, int lane, int wave) {
;     ...
;         for (int r = 0; r < 8; ++r) { float zc[8], bg[8], ov[8];
;             unpack8(*(const u32x4*)(Z + (size_t)(t0 + r) * 512 + c0), zc); unpack8(*(const u32x4*)(BG + (size_t)(t0 + r) * 512 + c0), bg);
; #pragma unroll
;             for (int i = 0; i < 8; ++i) { ov[i] = bg[i] * (w0[i] * z2[i] + w1[i] * z1[i] + w2[i] * zc[i]); z2[i] = z1[i]; z1[i] = zc[i]; }
;             st16wt(mix, (unsigned)(((t0 + r) * D_ + 512 + c0) * 2), pack8(ov)); }
	v_lshlrev_b32_e32 v116, 16, v52
	v_and_b32_e32 v117, 0xffff0000, v52
	v_lshlrev_b32_e32 v118, 16, v53
	v_and_b32_e32 v119, 0xffff0000, v53
	v_lshlrev_b32_e32 v120, 16, v54
	v_and_b32_e32 v121, 0xffff0000, v54
	v_lshlrev_b32_e32 v122, 16, v55
	v_and_b32_e32 v123, 0xffff0000, v55
	v_lshlrev_b32_e32 v132, 16, v56
	v_and_b32_e32 v133, 0xffff0000, v56
	v_lshlrev_b32_e32 v134, 16, v57
	v_and_b32_e32 v135, 0xffff0000, v57
	v_lshlrev_b32_e32 v136, 16, v58
	v_and_b32_e32 v137, 0xffff0000, v58
	v_lshlrev_b32_e32 v138, 16, v59
	v_and_b32_e32 v139, 0xffff0000, v59
	v_mul_f32_e32 v140, v16, v108
	v_mul_f32_e32 v141, v17, v109
	v_mul_f32_e32 v142, v18, v110
	v_mul_f32_e32 v143, v19, v111
	v_mul_f32_e32 v144, v20, v112
	v_mul_f32_e32 v145, v21, v113
	v_mul_f32_e32 v146, v22, v114
	v_mul_f32_e32 v147, v23, v115
	v_mul_f32_e32 v148, v24, v116
	v_mul_f32_e32 v149, v25, v117
	v_mul_f32_e32 v150, v26, v118
	v_mul_f32_e32 v151, v27, v119
	v_mul_f32_e32 v152, v28, v120
	v_mul_f32_e32 v153, v29, v121
	v_mul_f32_e32 v154, v30, v122
	v_mul_f32_e32 v155, v31, v123
	v_fma_f32 v140, v8, v124, v140
	v_fma_f32 v141, v9, v125, v141
	v_fma_f32 v142, v10, v126, v142
	v_fma_f32 v143, v11, v127, v143
	v_fma_f32 v144, v12, v128, v144
	v_fma_f32 v145, v13, v129, v145
	v_fma_f32 v146, v14, v130, v146
	v_fma_f32 v147, v15, v131, v147
	v_add_f32_e32 v140, v140, v148
	v_add_f32_e32 v141, v141, v149
	v_add_f32_e32 v142, v142, v150
	v_add_f32_e32 v143, v143, v151
	v_add_f32_e32 v144, v144, v152
	v_add_f32_e32 v145, v145, v153
	v_add_f32_e32 v146, v146, v154
	v_add_f32_e32 v147, v147, v155
	v_mul_f32_e32 v140, v140, v132
	v_mul_f32_e32 v141, v141, v133
	v_mul_f32_e32 v142, v142, v134
	v_mul_f32_e32 v143, v143, v135
	v_mul_f32_e32 v144, v144, v136
	v_mul_f32_e32 v145, v145, v137
	v_mul_f32_e32 v146, v146, v138
	v_mul_f32_e32 v147, v147, v139
	v_cvt_pk_bf16_f32 v160, v140, v141
	v_cvt_pk_bf16_f32 v161, v142, v143
	v_cvt_pk_bf16_f32 v162, v144, v145
	v_cvt_pk_bf16_f32 v163, v146, v147
	buffer_store_dwordx4 v[160:163], v35, s[8:11], 0 offen offset:2048 sc1
	s_waitcnt vmcnt(12)
	v_lshlrev_b32_e32 v124, 16, v60
	v_and_b32_e32 v125, 0xffff0000, v60
	v_lshlrev_b32_e32 v126, 16, v61
	v_and_b32_e32 v127, 0xffff0000, v61
	v_lshlrev_b32_e32 v128, 16, v62
	v_and_b32_e32 v129, 0xffff0000, v62
	v_lshlrev_b32_e32 v130, 16, v63
	v_and_b32_e32 v131, 0xffff0000, v63
	v_lshlrev_b32_e32 v132, 16, v64
	v_and_b32_e32 v133, 0xffff0000, v64
	v_lshlrev_b32_e32 v134, 16, v65
	v_and_b32_e32 v135, 0xffff0000, v65
	v_lshlrev_b32_e32 v136, 16, v66
	v_and_b32_e32 v137, 0xffff0000, v66
	v_lshlrev_b32_e32 v138, 16, v67
	v_and_b32_e32 v139, 0xffff0000, v67
	v_mul_f32_e32 v140, v16, v116
	v_mul_f32_e32 v141, v17, v117
	v_mul_f32_e32 v142, v18, v118
	v_mul_f32_e32 v143, v19, v119
	v_mul_f32_e32 v144, v20, v120
	v_mul_f32_e32 v145, v21, v121
	v_mul_f32_e32 v146, v22, v122
	v_mul_f32_e32 v147, v23, v123
	v_mul_f32_e32 v148, v24, v124
	v_mul_f32_e32 v149, v25, v125
	v_mul_f32_e32 v150, v26, v126
	v_mul_f32_e32 v151, v27, v127
	v_mul_f32_e32 v152, v28, v128
	v_mul_f32_e32 v153, v29, v129
	v_mul_f32_e32 v154, v30, v130
	v_mul_f32_e32 v155, v31, v131
	v_fma_f32 v140, v8, v108, v140
	v_fma_f32 v141, v9, v109, v141
	v_fma_f32 v142, v10, v110, v142
	v_fma_f32 v143, v11, v111, v143
	v_fma_f32 v144, v12, v112, v144
	v_fma_f32 v145, v13, v113, v145
	v_fma_f32 v146, v14, v114, v146
	v_fma_f32 v147, v15, v115, v147
	v_add_f32_e32 v140, v140, v148
	v_add_f32_e32 v141, v141, v149
	v_add_f32_e32 v142, v142, v150
	v_add_f32_e32 v143, v143, v151
	v_add_f32_e32 v144, v144, v152
	v_add_f32_e32 v145, v145, v153
	v_add_f32_e32 v146, v146, v154
	v_add_f32_e32 v147, v147, v155
	v_mul_f32_e32 v140, v140, v132
	v_mul_f32_e32 v141, v141, v133
	v_mul_f32_e32 v142, v142, v134
	v_mul_f32_e32 v143, v143, v135
	v_mul_f32_e32 v144, v144, v136
	v_mul_f32_e32 v145, v145, v137
	v_mul_f32_e32 v146, v146, v138
	v_mul_f32_e32 v147, v147, v139
	v_cvt_pk_bf16_f32 v156, v140, v141
	v_cvt_pk_bf16_f32 v157, v142, v143
	v_cvt_pk_bf16_f32 v158, v144, v145
	v_cvt_pk_bf16_f32 v159, v146, v147
	v_add_u32_e32 v35, 0x1000, v35
	buffer_store_dwordx4 v[156:159], v35, s[8:11], 0 offen sc1
	s_waitcnt vmcnt(11)
	v_lshlrev_b32_e32 v108, 16, v68
	v_and_b32_e32 v109, 0xffff0000, v68
	v_lshlrev_b32_e32 v110, 16, v69
	v_and_b32_e32 v111, 0xffff0000, v69
	v_lshlrev_b32_e32 v112, 16, v70
	v_and_b32_e32 v113, 0xffff0000, v70
	v_lshlrev_b32_e32 v114, 16, v71
	v_and_b32_e32 v115, 0xffff0000, v71
	v_lshlrev_b32_e32 v132, 16, v72
	v_and_b32_e32 v133, 0xffff0000, v72
	v_lshlrev_b32_e32 v134, 16, v73
	v_and_b32_e32 v135, 0xffff0000, v73
	v_lshlrev_b32_e32 v136, 16, v74
	v_and_b32_e32 v137, 0xffff0000, v74
	v_lshlrev_b32_e32 v138, 16, v75
	v_and_b32_e32 v139, 0xffff0000, v75
	v_mul_f32_e32 v140, v16, v124
	v_mul_f32_e32 v141, v17, v125
	v_mul_f32_e32 v142, v18, v126
	v_mul_f32_e32 v143, v19, v127
	v_mul_f32_e32 v144, v20, v128
	v_mul_f32_e32 v145, v21, v129
	v_mul_f32_e32 v146, v22, v130
	v_mul_f32_e32 v147, v23, v131
	v_mul_f32_e32 v148, v24, v108
	v_mul_f32_e32 v149, v25, v109
	v_mul_f32_e32 v150, v26, v110
	v_mul_f32_e32 v151, v27, v111
	v_mul_f32_e32 v152, v28, v112
	v_mul_f32_e32 v153, v29, v113
	v_mul_f32_e32 v154, v30, v114
	v_mul_f32_e32 v155, v31, v115
	v_fma_f32 v140, v8, v116, v140
	v_fma_f32 v141, v9, v117, v141
	v_fma_f32 v142, v10, v118, v142
	v_fma_f32 v143, v11, v119, v143
	v_fma_f32 v144, v12, v120, v144
	v_fma_f32 v145, v13, v121, v145
	v_fma_f32 v146, v14, v122, v146
	v_fma_f32 v147, v15, v123, v147
	v_add_f32_e32 v140, v140, v148
	v_add_f32_e32 v141, v141, v149
	v_add_f32_e32 v142, v142, v150
	v_add_f32_e32 v143, v143, v151
	v_add_f32_e32 v144, v144, v152
	v_add_f32_e32 v145, v145, v153
	v_add_f32_e32 v146, v146, v154
	v_add_f32_e32 v147, v147, v155
	v_mul_f32_e32 v140, v140, v132
	v_mul_f32_e32 v141, v141, v133
	v_mul_f32_e32 v142, v142, v134
	v_mul_f32_e32 v143, v143, v135
	v_mul_f32_e32 v144, v144, v136
	v_mul_f32_e32 v145, v145, v137
	v_mul_f32_e32 v146, v146, v138
	v_mul_f32_e32 v147, v147, v139
	v_cvt_pk_bf16_f32 v160, v140, v141
	v_cvt_pk_bf16_f32 v161, v142, v143
	v_cvt_pk_bf16_f32 v162, v144, v145
	v_cvt_pk_bf16_f32 v163, v146, v147
	buffer_store_dwordx4 v[160:163], v35, s[8:11], 0 offen offset:2048 sc1
	s_waitcnt vmcnt(10)
; __device__ __forceinline__ u32x4 pack8(const float (&f)[8]) { u32x4 w; w.x = pk2(f[0], f[1]); w.y = pk2(f[2], f[3]); w.z = pk2(f[4], f[5]); w.w = pk2(f[6], f[7]); return w; }
; __device__ __forceinline__ void phase3(const Params& p, LAS unsigned char* lds, int tid, int lane, int wave) {
;     ...
;         for (int r = 0; r < 8; ++r) { float zc[8], bg[8], ov[8];
;             unpack8(*(const u32x4*)(Z + (size_t)(t0 + r) * 512 + c0), zc); unpack8(*(const u32x4*)(BG + (size_t)(t0 + r) * 512 + c0), bg);
; #pragma unroll
;             for (int i = 0; i < 8; ++i) { ov[i] = bg[i] * (w0[i] * z2[i] + w1[i] * z1[i] + w2[i] * zc[i]); z2[i] = z1[i]; z1[i] = zc[i]; }
;             st16wt(mix, (unsigned)(((t0 + r) * D_ + 512 + c0) * 2), pack8(ov)); }
	v_lshlrev_b32_e32 v116, 16, v76
	v_and_b32_e32 v117, 0xffff0000, v76
	v_lshlrev_b32_e32 v118, 16, v77
	v_and_b32_e32 v119, 0xffff0000, v77
	v_lshlrev_b32_e32 v120, 16, v78
	v_and_b32_e32 v121, 0xffff0000, v78
	v_lshlrev_b32_e32 v122, 16, v79
	v_and_b32_e32 v123, 0xffff0000, v79
	v_lshlrev_b32_e32 v132, 16, v80
	v_and_b32_e32 v133, 0xffff0000, v80
	v_lshlrev_b32_e32 v134, 16, v81
	v_and_b32_e32 v135, 0xffff0000, v81
	v_lshlrev_b32_e32 v136, 16, v82
	v_and_b32_e32 v137, 0xffff0000, v82
	v_lshlrev_b32_e32 v138, 16, v83
	v_and_b32_e32 v139, 0xffff0000, v83
	v_mul_f32_e32 v140, v16, v108
	v_mul_f32_e32 v141, v17, v109
	v_mul_f32_e32 v142, v18, v110
	v_mul_f32_e32 v143, v19, v111
	v_mul_f32_e32 v144, v20, v112
	v_mul_f32_e32 v145, v21, v113
	v_mul_f32_e32 v146, v22, v114
	v_mul_f32_e32 v147, v23, v115
	v_mul_f32_e32 v148, v24, v116
	v_mul_f32_e32 v149, v25, v117
	v_mul_f32_e32 v150, v26, v118
	v_mul_f32_e32 v151, v27, v119
	v_mul_f32_e32 v152, v28, v120
	v_mul_f32_e32 v153, v29, v121
	v_mul_f32_e32 v154, v30, v122
	v_mul_f32_e32 v155, v31, v123
	v_fma_f32 v140, v8, v124, v140
	v_fma_f32 v141, v9, v125, v141
	v_fma_f32 v142, v10, v126, v142
	v_fma_f32 v143, v11, v127, v143
	v_fma_f32 v144, v12, v128, v144
	v_fma_f32 v145, v13, v129, v145
	v_fma_f32 v146, v14, v130, v146
	v_fma_f32 v147, v15, v131, v147
	v_add_f32_e32 v140, v140, v148
	v_add_f32_e32 v141, v141, v149
	v_add_f32_e32 v142, v142, v150
	v_add_f32_e32 v143, v143, v151
	v_add_f32_e32 v144, v144, v152
	v_add_f32_e32 v145, v145, v153
	v_add_f32_e32 v146, v146, v154
	v_add_f32_e32 v147, v147, v155
	v_mul_f32_e32 v140, v140, v132
	v_mul_f32_e32 v141, v141, v133
	v_mul_f32_e32 v142, v142, v134
	v_mul_f32_e32 v143, v143, v135
	v_mul_f32_e32 v144, v144, v136
	v_mul_f32_e32 v145, v145, v137
	v_mul_f32_e32 v146, v146, v138
	v_mul_f32_e32 v147, v147, v139
	v_cvt_pk_bf16_f32 v156, v140, v141
	v_cvt_pk_bf16_f32 v157, v142, v143
	v_cvt_pk_bf16_f32 v158, v144, v145
	v_cvt_pk_bf16_f32 v159, v146, v147
	v_add_u32_e32 v35, 0x1000, v35
	buffer_store_dwordx4 v[156:159], v35, s[8:11], 0 offen sc1
	s_waitcnt vmcnt(9)
	v_lshlrev_b32_e32 v124, 16, v84
	v_and_b32_e32 v125, 0xffff0000, v84
	v_lshlrev_b32_e32 v126, 16, v85
	v_and_b32_e32 v127, 0xffff0000, v85
	v_lshlrev_b32_e32 v128, 16, v86
	v_and_b32_e32 v129, 0xffff0000, v86
	v_lshlrev_b32_e32 v130, 16, v87
	v_and_b32_e32 v131, 0xffff0000, v87
	v_lshlrev_b32_e32 v132, 16, v88
	v_and_b32_e32 v133, 0xffff0000, v88
	v_lshlrev_b32_e32 v134, 16, v89
	v_and_b32_e32 v135, 0xffff0000, v89
	v_lshlrev_b32_e32 v136, 16, v90
	v_and_b32_e32 v137, 0xffff0000, v90
	v_lshlrev_b32_e32 v138, 16, v91
	v_and_b32_e32 v139, 0xffff0000, v91
	v_mul_f32_e32 v140, v16, v116
	v_mul_f32_e32 v141, v17, v117
	v_mul_f32_e32 v142, v18, v118
	v_mul_f32_e32 v143, v19, v119
	v_mul_f32_e32 v144, v20, v120
	v_mul_f32_e32 v145, v21, v121
	v_mul_f32_e32 v146, v22, v122
	v_mul_f32_e32 v147, v23, v123
	v_mul_f32_e32 v148, v24, v124
	v_mul_f32_e32 v149, v25, v125
	v_mul_f32_e32 v150, v26, v126
	v_mul_f32_e32 v151, v27, v127
	v_mul_f32_e32 v152, v28, v128
	v_mul_f32_e32 v153, v29, v129
	v_mul_f32_e32 v154, v30, v130
	v_mul_f32_e32 v155, v31, v131
	v_fma_f32 v140, v8, v108, v140
	v_fma_f32 v141, v9, v109, v141
	v_fma_f32 v142, v10, v110, v142
	v_fma_f32 v143, v11, v111, v143
	v_fma_f32 v144, v12, v112, v144
	v_fma_f32 v145, v13, v113, v145
	v_fma_f32 v146, v14, v114, v146
	v_fma_f32 v147, v15, v115, v147
	v_add_f32_e32 v140, v140, v148
	v_add_f32_e32 v141, v141, v149
	v_add_f32_e32 v142, v142, v150
	v_add_f32_e32 v143, v143, v151
	v_add_f32_e32 v144, v144, v152
	v_add_f32_e32 v145, v145, v153
	v_add_f32_e32 v146, v146, v154
	v_add_f32_e32 v147, v147, v155
	v_mul_f32_e32 v140, v140, v132
	v_mul_f32_e32 v141, v141, v133
	v_mul_f32_e32 v142, v142, v134
	v_mul_f32_e32 v143, v143, v135
	v_mul_f32_e32 v144, v144, v136
	v_mul_f32_e32 v145, v145, v137
	v_mul_f32_e32 v146, v146, v138
	v_mul_f32_e32 v147, v147, v139
	v_cvt_pk_bf16_f32 v160, v140, v141
	v_cvt_pk_bf16_f32 v161, v142, v143
	v_cvt_pk_bf16_f32 v162, v144, v145
	v_cvt_pk_bf16_f32 v163, v146, v147
	buffer_store_dwordx4 v[160:163], v35, s[8:11], 0 offen offset:2048 sc1
	s_waitcnt vmcnt(8)
; __device__ __forceinline__ u32x4 pack8(const float (&f)[8]) { u32x4 w; w.x = pk2(f[0], f[1]); w.y = pk2(f[2], f[3]); w.z = pk2(f[4], f[5]); w.w = pk2(f[6], f[7]); return w; }
; __device__ __forceinline__ void phase3(const Params& p, LAS unsigned char* lds, int tid, int lane, int wave) {
;     ...
;         for (int r = 0; r < 8; ++r) { float zc[8], bg[8], ov[8];
;             unpack8(*(const u32x4*)(Z + (size_t)(t0 + r) * 512 + c0), zc); unpack8(*(const u32x4*)(BG + (size_t)(t0 + r) * 512 + c0), bg);
; #pragma unroll
;             for (int i = 0; i < 8; ++i) { ov[i] = bg[i] * (w0[i] * z2[i] + w1[i] * z1[i] + w2[i] * zc[i]); z2[i] = z1[i]; z1[i] = zc[i]; }
;             st16wt(mix, (unsigned)(((t0 + r) * D_ + 512 + c0) * 2), pack8(ov)); }
	v_lshlrev_b32_e32 v108, 16, v92
	v_and_b32_e32 v109, 0xffff0000, v92
	v_lshlrev_b32_e32 v110, 16, v93
	v_and_b32_e32 v111, 0xffff0000, v93
	v_lshlrev_b32_e32 v112, 16, v94
	v_and_b32_e32 v113, 0xffff0000, v94
	v_lshlrev_b32_e32 v114, 16, v95
	v_and_b32_e32 v115, 0xffff0000, v95
	v_lshlrev_b32_e32 v132, 16, v96
	v_and_b32_e32 v133, 0xffff0000, v96
	v_lshlrev_b32_e32 v134, 16, v97
	v_and_b32_e32 v135, 0xffff0000, v97
	v_lshlrev_b32_e32 v136, 16, v98
	v_and_b32_e32 v137, 0xffff0000, v98
	v_lshlrev_b32_e32 v138, 16, v99
	v_and_b32_e32 v139, 0xffff0000, v99
	v_mul_f32_e32 v140, v16, v124
	v_mul_f32_e32 v141, v17, v125
	v_mul_f32_e32 v142, v18, v126
	v_mul_f32_e32 v143, v19, v127
	v_mul_f32_e32 v144, v20, v128
	v_mul_f32_e32 v145, v21, v129
	v_mul_f32_e32 v146, v22, v130
	v_mul_f32_e32 v147, v23, v131
	v_mul_f32_e32 v148, v24, v108
	v_mul_f32_e32 v149, v25, v109
	v_mul_f32_e32 v150, v26, v110
	v_mul_f32_e32 v151, v27, v111
	v_mul_f32_e32 v152, v28, v112
	v_mul_f32_e32 v153, v29, v113
	v_mul_f32_e32 v154, v30, v114
	v_mul_f32_e32 v155, v31, v115
	v_fma_f32 v140, v8, v116, v140
	v_fma_f32 v141, v9, v117, v141
	v_fma_f32 v142, v10, v118, v142
	v_fma_f32 v143, v11, v119, v143
	v_fma_f32 v144, v12, v120, v144
	v_fma_f32 v145, v13, v121, v145
	v_fma_f32 v146, v14, v122, v146
	v_fma_f32 v147, v15, v123, v147
	v_add_f32_e32 v140, v140, v148
	v_add_f32_e32 v141, v141, v149
	v_add_f32_e32 v142, v142, v150
	v_add_f32_e32 v143, v143, v151
	v_add_f32_e32 v144, v144, v152
	v_add_f32_e32 v145, v145, v153
	v_add_f32_e32 v146, v146, v154
	v_add_f32_e32 v147, v147, v155
	v_mul_f32_e32 v140, v140, v132
	v_mul_f32_e32 v141, v141, v133
	v_mul_f32_e32 v142, v142, v134
	v_mul_f32_e32 v143, v143, v135
	v_mul_f32_e32 v144, v144, v136
	v_mul_f32_e32 v145, v145, v137
	v_mul_f32_e32 v146, v146, v138
	v_mul_f32_e32 v147, v147, v139
	v_cvt_pk_bf16_f32 v156, v140, v141
	v_cvt_pk_bf16_f32 v157, v142, v143
	v_cvt_pk_bf16_f32 v158, v144, v145
	v_cvt_pk_bf16_f32 v159, v146, v147
	v_add_u32_e32 v35, 0x1000, v35
	buffer_store_dwordx4 v[156:159], v35, s[8:11], 0 offen sc1
	s_waitcnt vmcnt(7)
	v_lshlrev_b32_e32 v116, 16, v100
	v_and_b32_e32 v117, 0xffff0000, v100
	v_lshlrev_b32_e32 v118, 16, v101
	v_and_b32_e32 v119, 0xffff0000, v101
	v_lshlrev_b32_e32 v120, 16, v102
	v_and_b32_e32 v121, 0xffff0000, v102
	v_lshlrev_b32_e32 v122, 16, v103
	v_and_b32_e32 v123, 0xffff0000, v103
	v_lshlrev_b32_e32 v132, 16, v104
	v_and_b32_e32 v133, 0xffff0000, v104
	v_lshlrev_b32_e32 v134, 16, v105
	v_and_b32_e32 v135, 0xffff0000, v105
	v_lshlrev_b32_e32 v136, 16, v106
	v_and_b32_e32 v137, 0xffff0000, v106
	v_lshlrev_b32_e32 v138, 16, v107
	v_and_b32_e32 v139, 0xffff0000, v107
	v_mul_f32_e32 v140, v16, v108
	v_mul_f32_e32 v141, v17, v109
	v_mul_f32_e32 v142, v18, v110
	v_mul_f32_e32 v143, v19, v111
	v_mul_f32_e32 v144, v20, v112
	v_mul_f32_e32 v145, v21, v113
	v_mul_f32_e32 v146, v22, v114
	v_mul_f32_e32 v147, v23, v115
	v_mul_f32_e32 v148, v24, v116
	v_mul_f32_e32 v149, v25, v117
	v_mul_f32_e32 v150, v26, v118
	v_mul_f32_e32 v151, v27, v119
	v_mul_f32_e32 v152, v28, v120
	v_mul_f32_e32 v153, v29, v121
	v_mul_f32_e32 v154, v30, v122
	v_mul_f32_e32 v155, v31, v123
	v_fma_f32 v140, v8, v124, v140
	v_fma_f32 v141, v9, v125, v141
	v_fma_f32 v142, v10, v126, v142
	v_fma_f32 v143, v11, v127, v143
	v_fma_f32 v144, v12, v128, v144
	v_fma_f32 v145, v13, v129, v145
	v_fma_f32 v146, v14, v130, v146
	v_fma_f32 v147, v15, v131, v147
	v_add_f32_e32 v140, v140, v148
	v_add_f32_e32 v141, v141, v149
	v_add_f32_e32 v142, v142, v150
	v_add_f32_e32 v143, v143, v151
	v_add_f32_e32 v144, v144, v152
	v_add_f32_e32 v145, v145, v153
	v_add_f32_e32 v146, v146, v154
	v_add_f32_e32 v147, v147, v155
	v_mul_f32_e32 v140, v140, v132
	v_mul_f32_e32 v141, v141, v133
	v_mul_f32_e32 v142, v142, v134
	v_mul_f32_e32 v143, v143, v135
	v_mul_f32_e32 v144, v144, v136
	v_mul_f32_e32 v145, v145, v137
	v_mul_f32_e32 v146, v146, v138
	v_mul_f32_e32 v147, v147, v139
	v_cvt_pk_bf16_f32 v160, v140, v141
	v_cvt_pk_bf16_f32 v161, v142, v143
	v_cvt_pk_bf16_f32 v162, v144, v145
	v_cvt_pk_bf16_f32 v163, v146, v147
	buffer_store_dwordx4 v[160:163], v35, s[8:11], 0 offen offset:2048 sc1
	s_add_i32 s4, s4, s5
	s_branch .Lconv_loop
